# kernel tail: no grid barrier after the last step (workgroups exit after the final residual-norm stores)
# speedup vs baseline: 1.0025x; 1.0020x over previous
.LBB0_215:
	s_cmp_eq_u32 s65, 27
	s_cbranch_scc1 .LBB0_7
	v_readlane_b32 s4, v235, 46
	v_readlane_b32 s5, v235, 47
	v_readlane_b32 s46, v236, 13
	s_and_b64 vcc, exec, s[4:5]
	v_readlane_b32 s47, v236, 14
	s_waitcnt vmcnt(0)
	s_waitcnt lgkmcnt(0)
	s_barrier
	s_mov_b64 s[2:3], exec
	v_readlane_b32 s4, v238, 43
	v_readlane_b32 s5, v238, 44
	s_and_b64 s[4:5], s[2:3], s[4:5]
	s_mov_b64 exec, s[4:5]
	s_cbranch_execz .LBB0_269
	v_readlane_b32 s4, v235, 40
	s_waitcnt vmcnt(0) expcnt(0) lgkmcnt(0)
	s_nop 0
	v_mov_b32_e32 v0, s4
	ds_read_b32 v2, v0
	v_readlane_b32 s4, v235, 41
	s_waitcnt lgkmcnt(0)
	v_cmp_ne_u32_e32 vcc, 0, v2
	v_mov_b32_e32 v0, s4
	ds_read_b32 v0, v0
	s_cbranch_vccnz .LBB0_232
	s_mov_b32 s10, 1
	s_branch .LBB0_220
